# wave reductions in the conv LayerNorm and SGU mean statistics done with DPP row ops plus permlane16/32 swaps instead of six ds_bpermute round trips each (strategy 7: DPP for intra-wave movement)
# speedup vs baseline: 1.0195x; 1.0195x over previous
; #define LAS __attribute__((address_space(3)))
; __device__ __forceinline__ float bflo(unsigned w) { return __uint_as_float(w << 16); }
; __device__ __forceinline__ float bfhi(unsigned w) { return __uint_as_float(w & 0xffff0000u); }
; __device__ __forceinline__ float siluf_(float x) { return x * sigmoidf_(x); }
; __device__ __forceinline__ float wave_sum(float v) {
; #pragma unroll
;     for (int o = 1; o < 64; o <<= 1) v += __shfl_xor(v, o);
;     return v;
; }
; __device__ __forceinline__ void conv_item(KP p, LAS unsigned char* lds, int l, int tile) {
;     ...
;     for (int tt = 0; tt < 4; ++tt) { const int o = wid * 4 + tt; const size_t tok = (size_t)t0 + o;
;         f32x4 v[4]; float sm = 0.f;
; #pragma unroll
;         for (int j = 0; j < 4; ++j) { v[j] = *(const LAS f32x4*)(ybuf + o * 1024 + lane * 4 + 256 * j); sm += (v[j][0] + v[j][1]) + (v[j][2] + v[j][3]); }
;         const float mean = wave_sum(sm) * (1.f / 1024.f); float sq = 0.f;
; #pragma unroll
;         for (int j = 0; j < 4; ++j) { v[j] = v[j] - mean; sq += (v[j][0] * v[j][0] + v[j][1] * v[j][1]) + (v[j][2] * v[j][2] + v[j][3] * v[j][3]); }
;         const float rstd = rsqrtf(wave_sum(sq) * (1.f / 1024.f) + LN_EPS);
; #pragma unroll
;         for (int j = 0; j < 4; ++j) { const int c = lane * 4 + 256 * j;
;             const f32x4 gg = *(const f32x4*)(lng + c), bb = *(const f32x4*)(lnb + c);
;             const u32x2 gt = *(const u32x2*)(HM + tok * HMW + C_DGATE + c);
;             const f32x4 y = v[j] * rstd * gg + bb;
;             u32x2 wv; wv.x = pk2(siluf_(y[0]) * bflo(gt.x), siluf_(y[1]) * bfhi(gt.x)); wv.y = pk2(siluf_(y[2]) * bflo(gt.y), siluf_(y[3]) * bfhi(gt.y));
;             *(u32x2*)(YD + tok * 1024 + c) = wv; } }
.LBB0_464:
	v_add_u32_e32 v0, s6, v183
	ds_read_b128 v[14:17], v0
	ds_read_b128 v[10:13], v0 offset:1024
	ds_read_b128 v[6:9], v0 offset:2048
	s_mov_b64 s[42:43], 0x4200
	s_addk_i32 s6, 0x1000
	global_load_dwordx2 v[228:229], v[160:161], off offset:-1024
	global_load_dwordx2 v[230:231], v[160:161], off offset:-512
	global_load_dwordx2 v[232:233], v[160:161], off
	global_load_dwordx2 v[234:235], v[160:161], off offset:512
	v_lshl_add_u64 v[160:161], v[160:161], 0, s[42:43]
	s_waitcnt lgkmcnt(2)
	v_mov_b32_e32 v2, v15
	v_mov_b32_e32 v3, v16
	v_mov_b32_e32 v4, v14
	v_mov_b32_e32 v5, v17
	v_pk_add_f32 v[2:3], v[2:3], v[4:5]
	s_waitcnt lgkmcnt(1)
	v_mov_b32_e32 v4, v10
	v_add_f32_e32 v2, v2, v3
	v_add_f32_e32 v164, 0, v2
	v_mov_b32_e32 v2, v11
	v_mov_b32_e32 v3, v12
	v_mov_b32_e32 v5, v13
	v_pk_add_f32 v[2:3], v[2:3], v[4:5]
	s_cmpk_eq_i32 s6, 0x4000
	v_pk_add_f32 v[186:187], v[2:3], v[2:3] op_sel:[0,1] op_sel_hi:[1,0]
	ds_read_b128 v[2:5], v0 offset:3072
	s_waitcnt lgkmcnt(1)
	v_add_f32_e32 v188, v6, v7
	v_add_f32_e32 v190, v8, v9
	s_waitcnt lgkmcnt(0)
	v_mov_b32_e32 v165, v2
	v_mov_b32_e32 v187, v3
	v_mov_b32_e32 v189, v4
	v_mov_b32_e32 v191, v5
	v_pk_add_f32 v[164:165], v[164:165], v[186:187]
	v_pk_add_f32 v[186:187], v[188:189], v[190:191]
	s_nop 0
	v_pk_add_f32 v[164:165], v[164:165], v[186:187]
	s_nop 0
	v_add_f32_e32 v0, v164, v165
	s_nop 1
	v_add_f32_dpp v0, v0, v0 quad_perm:[1,0,3,2] row_mask:0xf bank_mask:0xf
	s_nop 1
	v_add_f32_dpp v0, v0, v0 quad_perm:[2,3,0,1] row_mask:0xf bank_mask:0xf
	s_nop 1
	v_add_f32_dpp v0, v0, v0 row_half_mirror row_mask:0xf bank_mask:0xf
	s_nop 1
	v_add_f32_dpp v0, v0, v0 row_mirror row_mask:0xf bank_mask:0xf
	v_mov_b32_e32 v164, v0
	s_nop 1
	v_permlane16_swap_b32_e32 v0, v164
	v_add_f32_e32 v0, v0, v164
	v_mov_b32_e32 v164, v0
	s_nop 1
	v_permlane32_swap_b32_e32 v0, v164
	v_add_f32_e32 v192, v0, v164
	v_fmamk_f32 v15, v192, 0xba800000, v15
	v_fmamk_f32 v14, v192, 0xba800000, v14
	v_fmamk_f32 v17, v192, 0xba800000, v17
	v_fmac_f32_e32 v16, 0xba800000, v192
	v_pk_mul_f32 v[164:165], v[16:17], v[16:17]
	v_pk_mul_f32 v[186:187], v[14:15], v[14:15]
	v_fmamk_f32 v11, v192, 0xba800000, v11
	v_pk_mov_b32 v[188:189], v[186:187], v[164:165] op_sel:[1,0]
	v_mov_b32_e32 v187, v165
	v_fmamk_f32 v10, v192, 0xba800000, v10
	v_fmamk_f32 v13, v192, 0xba800000, v13
	v_fmac_f32_e32 v12, 0xba800000, v192
	v_pk_add_f32 v[164:165], v[188:189], v[186:187]
	v_pk_mul_f32 v[186:187], v[12:13], v[12:13]
	v_pk_mul_f32 v[188:189], v[10:11], v[10:11]
	v_fmamk_f32 v6, v192, 0xba800000, v6
	v_pk_mov_b32 v[190:191], v[188:189], v[186:187] op_sel:[1,0]
	v_mov_b32_e32 v189, v187
	v_fmamk_f32 v7, v192, 0xba800000, v7
	v_fmac_f32_e32 v8, 0xba800000, v192
	v_mul_f32_e32 v0, v6, v6
	v_pk_add_f32 v[186:187], v[190:191], v[188:189]
	v_fmamk_f32 v9, v192, 0xba800000, v9
	v_pk_fma_f32 v[188:189], v[6:7], v[6:7], v[0:1] op_sel_hi:[1,1,0]
	v_mul_f32_e32 v0, v8, v8
	v_pk_add_f32 v[164:165], v[164:165], v[164:165] op_sel_hi:[0,1]
	v_pk_add_f32 v[186:187], v[186:187], v[186:187] op_sel_hi:[0,1]
	v_pk_fma_f32 v[190:191], v[8:9], v[8:9], v[0:1] op_sel_hi:[1,1,0]
	v_fmamk_f32 v5, v192, 0xba800000, v5
	v_fmamk_f32 v4, v192, 0xba800000, v4
	v_fmamk_f32 v3, v192, 0xba800000, v3
	v_fmac_f32_e32 v2, 0xba800000, v192
	v_mul_f32_e32 v188, v2, v2
	v_mul_f32_e32 v190, v3, v3
	v_mul_f32_e32 v164, v4, v4
	v_mul_f32_e32 v186, v5, v5
	v_pk_add_f32 v[188:189], v[188:189], v[190:191]
	v_pk_add_f32 v[164:165], v[164:165], v[186:187]
	s_nop 0
	v_pk_add_f32 v[164:165], v[188:189], v[164:165]
	s_nop 0
	v_add_f32_e32 v0, v164, v165
	s_nop 1
	v_add_f32_dpp v0, v0, v0 quad_perm:[1,0,3,2] row_mask:0xf bank_mask:0xf
	s_nop 1
	v_add_f32_dpp v0, v0, v0 quad_perm:[2,3,0,1] row_mask:0xf bank_mask:0xf
	s_nop 1
	v_add_f32_dpp v0, v0, v0 row_half_mirror row_mask:0xf bank_mask:0xf
	s_nop 1
	v_add_f32_dpp v0, v0, v0 row_mirror row_mask:0xf bank_mask:0xf
	v_mov_b32_e32 v164, v0
	s_nop 1
	v_permlane16_swap_b32_e32 v0, v164
	v_add_f32_e32 v0, v0, v164
	v_mov_b32_e32 v164, v0
	s_nop 1
	v_permlane32_swap_b32_e32 v0, v164
	v_add_f32_e32 v0, v0, v164
	v_fmamk_f32 v0, v0, 0x3a800000, v169
	v_cmp_gt_f32_e32 vcc, s56, v0
	v_mul_f32_e32 v164, 0x4b800000, v0
	s_nop 0
	v_cndmask_b32_e32 v0, v0, v164, vcc
	v_rsq_f32_e32 v0, v0
	s_nop 0
	v_mul_f32_e32 v164, 0x45800000, v0
	v_cndmask_b32_e32 v0, v0, v164, vcc
	v_pk_mul_f32 v[14:15], v[14:15], v[0:1] op_sel_hi:[1,0]
	v_pk_mul_f32 v[16:17], v[16:17], v[0:1] op_sel_hi:[1,0]
	v_pk_mul_f32 v[10:11], v[10:11], v[0:1] op_sel_hi:[1,0]
	v_pk_mul_f32 v[12:13], v[12:13], v[0:1] op_sel_hi:[1,0]
	v_pk_mul_f32 v[6:7], v[6:7], v[0:1] op_sel_hi:[1,0]
	v_pk_mul_f32 v[8:9], v[8:9], v[0:1] op_sel_hi:[1,0]
	v_pk_mul_f32 v[2:3], v[2:3], v[0:1] op_sel_hi:[1,0]
	v_pk_mul_f32 v[4:5], v[4:5], v[0:1] op_sel_hi:[1,0]
	v_pk_fma_f32 v[14:15], v[196:197], v[14:15], v[200:201]
	v_pk_fma_f32 v[16:17], v[198:199], v[16:17], v[202:203]
	v_mul_f32_e32 v186, 0xbfb8aa3b, v14
	v_mul_f32_e32 v187, 0xbfb8aa3b, v15
	v_mul_f32_e32 v188, 0xbfb8aa3b, v16
	v_mul_f32_e32 v189, 0xbfb8aa3b, v17
	v_exp_f32_e32 v186, v186
	v_exp_f32_e32 v187, v187
	v_exp_f32_e32 v188, v188
	v_exp_f32_e32 v189, v189
	v_add_f32_e32 v186, 1.0, v186
	v_add_f32_e32 v187, 1.0, v187
	v_add_f32_e32 v188, 1.0, v188
	v_add_f32_e32 v189, 1.0, v189
	v_rcp_f32_e32 v186, v186
	v_rcp_f32_e32 v187, v187
	v_rcp_f32_e32 v188, v188
	v_rcp_f32_e32 v189, v189
	s_waitcnt vmcnt(3)
; __device__ __forceinline__ float bflo(unsigned w) { return __uint_as_float(w << 16); }
; __device__ __forceinline__ float bfhi(unsigned w) { return __uint_as_float(w & 0xffff0000u); }
; __device__ __forceinline__ float siluf_(float x) { return x * sigmoidf_(x); }
; __device__ __forceinline__ void conv_item(KP p, LAS unsigned char* lds, int l, int tile) {
;     ...
;         for (int j = 0; j < 4; ++j) { const int c = lane * 4 + 256 * j;
;             const f32x4 gg = *(const f32x4*)(lng + c), bb = *(const f32x4*)(lnb + c);
;             const u32x2 gt = *(const u32x2*)(HM + tok * HMW + C_DGATE + c);
;             const f32x4 y = v[j] * rstd * gg + bb;
;             u32x2 wv; wv.x = pk2(siluf_(y[0]) * bflo(gt.x), siluf_(y[1]) * bfhi(gt.x)); wv.y = pk2(siluf_(y[2]) * bflo(gt.y), siluf_(y[3]) * bfhi(gt.y));
;             *(u32x2*)(YD + tok * 1024 + c) = wv; } }
;     __syncthreads();
	v_lshlrev_b32_e32 v190, 16, v228
	v_and_b32_e32 v191, 0xffff0000, v228
	v_lshlrev_b32_e32 v192, 16, v229
	v_and_b32_e32 v193, 0xffff0000, v229
	v_pk_mul_f32 v[14:15], v[14:15], v[186:187]
	v_pk_mul_f32 v[16:17], v[16:17], v[188:189]
	v_pk_mul_f32 v[14:15], v[14:15], v[190:191]
	v_pk_mul_f32 v[16:17], v[16:17], v[192:193]
	v_cvt_pk_bf16_f32 v14, v14, v15
	v_cvt_pk_bf16_f32 v15, v16, v17
	global_store_dwordx2 v[162:163], v[14:15], off offset:-1024
	v_pk_fma_f32 v[10:11], v[204:205], v[10:11], v[208:209]
	v_pk_fma_f32 v[12:13], v[206:207], v[12:13], v[210:211]
	v_mul_f32_e32 v186, 0xbfb8aa3b, v10
	v_mul_f32_e32 v187, 0xbfb8aa3b, v11
	v_mul_f32_e32 v188, 0xbfb8aa3b, v12
	v_mul_f32_e32 v189, 0xbfb8aa3b, v13
	v_exp_f32_e32 v186, v186
	v_exp_f32_e32 v187, v187
	v_exp_f32_e32 v188, v188
	v_exp_f32_e32 v189, v189
	v_add_f32_e32 v186, 1.0, v186
	v_add_f32_e32 v187, 1.0, v187
	v_add_f32_e32 v188, 1.0, v188
	v_add_f32_e32 v189, 1.0, v189
	v_rcp_f32_e32 v186, v186
	v_rcp_f32_e32 v187, v187
	v_rcp_f32_e32 v188, v188
	v_rcp_f32_e32 v189, v189
	s_waitcnt vmcnt(3)
	v_lshlrev_b32_e32 v190, 16, v230
	v_and_b32_e32 v191, 0xffff0000, v230
	v_lshlrev_b32_e32 v192, 16, v231
	v_and_b32_e32 v193, 0xffff0000, v231
	v_pk_mul_f32 v[10:11], v[10:11], v[186:187]
	v_pk_mul_f32 v[12:13], v[12:13], v[188:189]
	v_pk_mul_f32 v[10:11], v[10:11], v[190:191]
	v_pk_mul_f32 v[12:13], v[12:13], v[192:193]
	v_cvt_pk_bf16_f32 v10, v10, v11
	v_cvt_pk_bf16_f32 v11, v12, v13
	global_store_dwordx2 v[162:163], v[10:11], off offset:-512
	v_pk_fma_f32 v[6:7], v[212:213], v[6:7], v[216:217]
	v_pk_fma_f32 v[8:9], v[214:215], v[8:9], v[218:219]
	v_mul_f32_e32 v186, 0xbfb8aa3b, v6
	v_mul_f32_e32 v187, 0xbfb8aa3b, v7
	v_mul_f32_e32 v188, 0xbfb8aa3b, v8
	v_mul_f32_e32 v189, 0xbfb8aa3b, v9
	v_exp_f32_e32 v186, v186
	v_exp_f32_e32 v187, v187
	v_exp_f32_e32 v188, v188
	v_exp_f32_e32 v189, v189
	v_add_f32_e32 v186, 1.0, v186
	v_add_f32_e32 v187, 1.0, v187
	v_add_f32_e32 v188, 1.0, v188
	v_add_f32_e32 v189, 1.0, v189
	v_rcp_f32_e32 v186, v186
	v_rcp_f32_e32 v187, v187
	v_rcp_f32_e32 v188, v188
	v_rcp_f32_e32 v189, v189
	s_waitcnt vmcnt(3)
	v_lshlrev_b32_e32 v190, 16, v232
	v_and_b32_e32 v191, 0xffff0000, v232
	v_lshlrev_b32_e32 v192, 16, v233
	v_and_b32_e32 v193, 0xffff0000, v233
	v_pk_mul_f32 v[6:7], v[6:7], v[186:187]
	v_pk_mul_f32 v[8:9], v[8:9], v[188:189]
	v_pk_mul_f32 v[6:7], v[6:7], v[190:191]
	v_pk_mul_f32 v[8:9], v[8:9], v[192:193]
	v_cvt_pk_bf16_f32 v6, v6, v7
	v_cvt_pk_bf16_f32 v7, v8, v9
	global_store_dwordx2 v[162:163], v[6:7], off
	v_pk_fma_f32 v[2:3], v[220:221], v[2:3], v[224:225]
	v_pk_fma_f32 v[4:5], v[222:223], v[4:5], v[226:227]
	v_mul_f32_e32 v186, 0xbfb8aa3b, v2
	v_mul_f32_e32 v187, 0xbfb8aa3b, v3
	v_mul_f32_e32 v188, 0xbfb8aa3b, v4
	v_mul_f32_e32 v189, 0xbfb8aa3b, v5
	v_exp_f32_e32 v186, v186
	v_exp_f32_e32 v187, v187
	v_exp_f32_e32 v188, v188
	v_exp_f32_e32 v189, v189
	v_add_f32_e32 v186, 1.0, v186
	v_add_f32_e32 v187, 1.0, v187
	v_add_f32_e32 v188, 1.0, v188
	v_add_f32_e32 v189, 1.0, v189
	v_rcp_f32_e32 v186, v186
	v_rcp_f32_e32 v187, v187
	v_rcp_f32_e32 v188, v188
	v_rcp_f32_e32 v189, v189
	s_waitcnt vmcnt(3)
	v_lshlrev_b32_e32 v190, 16, v234
	v_and_b32_e32 v191, 0xffff0000, v234
	v_lshlrev_b32_e32 v192, 16, v235
	v_and_b32_e32 v193, 0xffff0000, v235
	v_pk_mul_f32 v[2:3], v[2:3], v[186:187]
	v_pk_mul_f32 v[4:5], v[4:5], v[188:189]
	v_pk_mul_f32 v[2:3], v[2:3], v[190:191]
	v_pk_mul_f32 v[4:5], v[4:5], v[192:193]
	v_cvt_pk_bf16_f32 v2, v2, v3
	v_cvt_pk_bf16_f32 v3, v4, v5
	global_store_dwordx2 v[162:163], v[2:3], off offset:512
	s_mov_b64 s[42:43], 0x800
	v_lshl_add_u64 v[162:163], v[162:163], 0, s[42:43]
	s_cbranch_scc0 .LBB0_464
	s_mov_b32 s63, 32
	s_mov_b64 s[44:45], 0
	s_mov_b64 s[42:43], -1
	s_and_b64 vcc, exec, s[40:41]
	s_barrier
	s_cbranch_vccz .LBB0_461

; __device__ __forceinline__ float bflo(unsigned w) { return __uint_as_float(w << 16); }
; __device__ __forceinline__ float bfhi(unsigned w) { return __uint_as_float(w & 0xffff0000u); }
; __device__ __forceinline__ void sgu_item(KP p, LAS unsigned char* lds, int l, int n) {
;     ...
;         for (int q = 0; q < 4; ++q) { const bf16_t* row = HM + (size_t)(n * 128 + wid * 16 + tb + q) * HMW + C_V; a[q] = *(const u32x4*)(row + lane * 8); b[q] = *(const u32x4*)(row + 512 + lane * 8); }
;         float mean[4], rstd[4];
; #pragma unroll
;         for (int q = 0; q < 4; ++q) { const float sm = ((bflo(a[q].x) + bfhi(a[q].x)) + (bflo(a[q].y) + bfhi(a[q].y))) + ((bflo(a[q].z) + bfhi(a[q].z)) + (bflo(a[q].w) + bfhi(a[q].w)))
;                 + ((bflo(b[q].x) + bfhi(b[q].x)) + (bflo(b[q].y) + bfhi(b[q].y))) + ((bflo(b[q].z) + bfhi(b[q].z)) + (bflo(b[q].w) + bfhi(b[q].w)));
;             mean[q] = sm; }
; #pragma unroll
;         for (int o = 1; o < 64; o <<= 1) {
; #pragma unroll
;             for (int q = 0; q < 4; ++q) mean[q] += __shfl_xor(mean[q], o); }
; #pragma unroll
;         for (int q = 0; q < 4; ++q) { mean[q] *= (1.f / 1024.f); const float m = mean[q];
;             const float d0 = bflo(a[q].x) - m, d1 = bfhi(a[q].x) - m, d2 = bflo(a[q].y) - m, d3 = bfhi(a[q].y) - m, d4 = bflo(a[q].z) - m, d5 = bfhi(a[q].z) - m, d6 = bflo(a[q].w) - m, d7 = bfhi(a[q].w) - m;
;             const float e0 = bflo(b[q].x) - m, e1 = bfhi(b[q].x) - m, e2 = bflo(b[q].y) - m, e3 = bfhi(b[q].y) - m, e4 = bflo(b[q].z) - m, e5 = bfhi(b[q].z) - m, e6 = bflo(b[q].w) - m, e7 = bfhi(b[q].w) - m;
;             rstd[q] = ((d0 * d0 + d1 * d1) + (d2 * d2 + d3 * d3)) + ((d4 * d4 + d5 * d5) + (d6 * d6 + d7 * d7)) + ((e0 * e0 + e1 * e1) + (e2 * e2 + e3 * e3)) + ((e4 * e4 + e5 * e5) + (e6 * e6 + e7 * e7)); }
.LBB0_520:
	v_add_co_u32_e32 v2, vcc, 0xffff4000, v20
	s_movk_i32 s24, 0xc000
	s_nop 0
	v_addc_co_u32_e32 v3, vcc, -1, v21, vcc
	global_load_dwordx4 v[22:25], v[2:3], off offset:-2560
	global_load_dwordx4 v[26:29], v[2:3], off offset:-1536
	v_add_co_u32_e32 v2, vcc, 0xffff8000, v20
	s_waitcnt vmcnt(1)
	v_and_b32_e32 v53, 0xffff0000, v24
	v_addc_co_u32_e32 v3, vcc, -1, v21, vcc
	global_load_dwordx4 v[30:33], v[2:3], off offset:-2048
	global_load_dwordx4 v[34:37], v[2:3], off offset:-1024
	v_add_co_u32_e32 v6, vcc, s24, v20
	s_waitcnt vmcnt(2)
	v_and_b32_e32 v39, 0xffff0000, v29
	v_addc_co_u32_e32 v7, vcc, -1, v21, vcc
	global_load_dwordx4 v[2:5], v[6:7], off offset:-1536
	s_waitcnt lgkmcnt(0)
	global_load_dwordx4 v[10:13], v[6:7], off offset:-512
	s_nop 0
	global_load_dwordx4 v[6:9], v[20:21], off offset:-1024
	global_load_dwordx4 v[14:17], v[20:21], off
	v_lshlrev_b32_e32 v41, 16, v29
	v_and_b32_e32 v45, 0xffff0000, v28
	v_lshlrev_b32_e32 v29, 16, v28
	v_and_b32_e32 v47, 0xffff0000, v27
	v_lshlrev_b32_e32 v49, 16, v26
	v_lshlrev_b32_e32 v55, 16, v25
	v_and_b32_e32 v25, 0xffff0000, v25
	v_and_b32_e32 v63, 0xffff0000, v22
	v_lshlrev_b32_e32 v65, 16, v23
	v_and_b32_e32 v67, 0xffff0000, v23
	s_waitcnt vmcnt(5)
	v_and_b32_e32 v52, 0xffff0000, v32
	s_waitcnt vmcnt(4)
	v_and_b32_e32 v38, 0xffff0000, v37
	v_lshlrev_b32_e32 v40, 16, v37
	v_and_b32_e32 v44, 0xffff0000, v36
	v_lshlrev_b32_e32 v28, 16, v36
	v_pk_add_f32 v[42:43], v[40:41], v[38:39]
	v_pk_add_f32 v[36:37], v[28:29], v[44:45]
	v_and_b32_e32 v46, 0xffff0000, v35
	v_pk_add_f32 v[36:37], v[36:37], v[42:43]
	v_lshlrev_b32_e32 v43, 16, v27
	v_lshlrev_b32_e32 v42, 16, v35
	v_lshlrev_b32_e32 v48, 16, v34
	v_and_b32_e32 v27, 0xffff0000, v26
	v_and_b32_e32 v26, 0xffff0000, v34
	v_pk_add_f32 v[34:35], v[42:43], v[46:47]
	v_pk_add_f32 v[50:51], v[48:49], v[26:27]
	v_lshlrev_b32_e32 v54, 16, v33
	v_pk_add_f32 v[34:35], v[50:51], v[34:35]
	v_lshlrev_b32_e32 v51, 16, v24
	v_lshlrev_b32_e32 v50, 16, v32
	v_and_b32_e32 v24, 0xffff0000, v33
	v_lshlrev_b32_e32 v33, 16, v22
	v_lshlrev_b32_e32 v32, 16, v30
	v_and_b32_e32 v62, 0xffff0000, v30
	v_lshlrev_b32_e32 v64, 16, v31
	v_and_b32_e32 v66, 0xffff0000, v31
	v_pk_add_f32 v[22:23], v[50:51], v[52:53]
	v_pk_add_f32 v[30:31], v[54:55], v[24:25]
	v_pk_add_f32 v[68:69], v[64:65], v[66:67]
	v_pk_add_f32 v[22:23], v[22:23], v[30:31]
	v_pk_add_f32 v[30:31], v[32:33], v[62:63]
	s_nop 0
	v_pk_add_f32 v[30:31], v[30:31], v[68:69]
	s_waitcnt vmcnt(3)
	v_and_b32_e32 v69, 0xffff0000, v3
	v_pk_add_f32 v[22:23], v[30:31], v[22:23]
	s_waitcnt vmcnt(1)
	v_and_b32_e32 v68, 0xffff0000, v7
	v_pk_add_f32 v[22:23], v[22:23], v[34:35]
	s_nop 0
	v_pk_add_f32 v[22:23], v[36:37], v[22:23]
	s_nop 1
	v_add_f32_dpp v22, v22, v22 quad_perm:[1,0,3,2] row_mask:0xf bank_mask:0xf
	v_add_f32_dpp v23, v23, v23 quad_perm:[1,0,3,2] row_mask:0xf bank_mask:0xf
	s_nop 0
	v_add_f32_dpp v22, v22, v22 quad_perm:[2,3,0,1] row_mask:0xf bank_mask:0xf
	v_add_f32_dpp v23, v23, v23 quad_perm:[2,3,0,1] row_mask:0xf bank_mask:0xf
	s_nop 0
	v_add_f32_dpp v22, v22, v22 row_half_mirror row_mask:0xf bank_mask:0xf
	v_add_f32_dpp v23, v23, v23 row_half_mirror row_mask:0xf bank_mask:0xf
	s_nop 0
	v_add_f32_dpp v22, v22, v22 row_mirror row_mask:0xf bank_mask:0xf
	v_add_f32_dpp v23, v23, v23 row_mirror row_mask:0xf bank_mask:0xf
	s_nop 0
	v_mov_b32_e32 v30, v22
	v_mov_b32_e32 v31, v23
	s_nop 1
	v_permlane16_swap_b32_e32 v22, v30
	v_permlane16_swap_b32_e32 v23, v31
	v_pk_add_f32 v[22:23], v[22:23], v[30:31]
	s_nop 0
	v_mov_b32_e32 v30, v22
	v_mov_b32_e32 v31, v23
	s_nop 1
	v_permlane32_swap_b32_e32 v22, v30
	v_permlane32_swap_b32_e32 v23, v31
	v_pk_add_f32 v[22:23], v[22:23], v[30:31]
	s_nop 0
	v_pk_fma_f32 v[30:31], v[22:23], s[12:13], v[32:33] op_sel_hi:[1,0,1] neg_lo:[1,0,0] neg_hi:[1,0,0]
	v_pk_fma_f32 v[32:33], v[22:23], s[12:13], v[62:63] op_sel_hi:[1,0,1] neg_lo:[1,0,0] neg_hi:[1,0,0]
	v_pk_fma_f32 v[36:37], v[22:23], s[12:13], v[66:67] op_sel_hi:[1,0,1] neg_lo:[1,0,0] neg_hi:[1,0,0]
	v_pk_fma_f32 v[62:63], v[22:23], s[12:13], v[24:25] op_sel_hi:[1,0,1] neg_lo:[1,0,0] neg_hi:[1,0,0]
	v_pk_fma_f32 v[24:25], v[22:23], s[12:13], v[28:29] op_sel_hi:[1,0,1] neg_lo:[1,0,0] neg_hi:[1,0,0]
	v_pk_mul_f32 v[28:29], v[32:33], v[32:33]
	v_pk_fma_f32 v[34:35], v[22:23], s[12:13], v[64:65] op_sel_hi:[1,0,1] neg_lo:[1,0,0] neg_hi:[1,0,0]
	v_pk_fma_f32 v[28:29], v[30:31], v[30:31], v[28:29]
	v_pk_mul_f32 v[30:31], v[36:37], v[36:37]
	v_pk_fma_f32 v[52:53], v[22:23], s[12:13], v[52:53] op_sel_hi:[1,0,1] neg_lo:[1,0,0] neg_hi:[1,0,0]
	v_pk_fma_f32 v[46:47], v[22:23], s[12:13], v[46:47] op_sel_hi:[1,0,1] neg_lo:[1,0,0] neg_hi:[1,0,0]
	v_pk_fma_f32 v[30:31], v[34:35], v[34:35], v[30:31]
	v_pk_fma_f32 v[50:51], v[22:23], s[12:13], v[50:51] op_sel_hi:[1,0,1] neg_lo:[1,0,0] neg_hi:[1,0,0]
	v_pk_fma_f32 v[54:55], v[22:23], s[12:13], v[54:55] op_sel_hi:[1,0,1] neg_lo:[1,0,0] neg_hi:[1,0,0]
	v_pk_fma_f32 v[64:65], v[22:23], s[12:13], v[26:27] op_sel_hi:[1,0,1] neg_lo:[1,0,0] neg_hi:[1,0,0]
	v_pk_fma_f32 v[42:43], v[22:23], s[12:13], v[42:43] op_sel_hi:[1,0,1] neg_lo:[1,0,0] neg_hi:[1,0,0]
	v_pk_fma_f32 v[44:45], v[22:23], s[12:13], v[44:45] op_sel_hi:[1,0,1] neg_lo:[1,0,0] neg_hi:[1,0,0]
	v_pk_fma_f32 v[26:27], v[22:23], s[12:13], v[40:41] op_sel_hi:[1,0,1] neg_lo:[1,0,0] neg_hi:[1,0,0]
	v_pk_fma_f32 v[40:41], v[22:23], s[12:13], v[38:39] op_sel_hi:[1,0,1] neg_lo:[1,0,0] neg_hi:[1,0,0]
	v_pk_add_f32 v[28:29], v[28:29], v[30:31]
	v_pk_mul_f32 v[30:31], v[52:53], v[52:53]
	v_pk_mul_f32 v[32:33], v[62:63], v[62:63]
	v_pk_mul_f32 v[34:35], v[46:47], v[46:47]
	v_pk_fma_f32 v[30:31], v[50:51], v[50:51], v[30:31]
	v_pk_fma_f32 v[32:33], v[54:55], v[54:55], v[32:33]
	v_pk_fma_f32 v[38:39], v[42:43], v[42:43], v[34:35]
	v_pk_mul_f32 v[34:35], v[44:45], v[44:45]
	v_pk_mul_f32 v[36:37], v[40:41], v[40:41]
	v_and_b32_e32 v41, 0xffff0000, v13
	s_waitcnt vmcnt(0)
; __device__ __forceinline__ float bflo(unsigned w) { return __uint_as_float(w << 16); }
; __device__ __forceinline__ float bfhi(unsigned w) { return __uint_as_float(w & 0xffff0000u); }
; __device__ __forceinline__ void sgu_item(KP p, LAS unsigned char* lds, int l, int n) {
;     ...
; #pragma unroll
;         for (int q = 0; q < 4; ++q) { const float sm = ((bflo(a[q].x) + bfhi(a[q].x)) + (bflo(a[q].y) + bfhi(a[q].y))) + ((bflo(a[q].z) + bfhi(a[q].z)) + (bflo(a[q].w) + bfhi(a[q].w)))
;                 + ((bflo(b[q].x) + bfhi(b[q].x)) + (bflo(b[q].y) + bfhi(b[q].y))) + ((bflo(b[q].z) + bfhi(b[q].z)) + (bflo(b[q].w) + bfhi(b[q].w)));
;             mean[q] = sm; }
; #pragma unroll
;         for (int o = 1; o < 64; o <<= 1) {
; #pragma unroll
;             for (int q = 0; q < 4; ++q) mean[q] += __shfl_xor(mean[q], o); }
; #pragma unroll
;         for (int q = 0; q < 4; ++q) { mean[q] *= (1.f / 1024.f); const float m = mean[q];
;             const float d0 = bflo(a[q].x) - m, d1 = bfhi(a[q].x) - m, d2 = bflo(a[q].y) - m, d3 = bfhi(a[q].y) - m, d4 = bflo(a[q].z) - m, d5 = bfhi(a[q].z) - m, d6 = bflo(a[q].w) - m, d7 = bfhi(a[q].w) - m;
;             const float e0 = bflo(b[q].x) - m, e1 = bfhi(b[q].x) - m, e2 = bflo(b[q].y) - m, e3 = bfhi(b[q].y) - m, e4 = bflo(b[q].z) - m, e5 = bfhi(b[q].z) - m, e6 = bflo(b[q].w) - m, e7 = bfhi(b[q].w) - m;
;             rstd[q] = ((d0 * d0 + d1 * d1) + (d2 * d2 + d3 * d3)) + ((d4 * d4 + d5 * d5) + (d6 * d6 + d7 * d7)) + ((e0 * e0 + e1 * e1) + (e2 * e2 + e3 * e3)) + ((e4 * e4 + e5 * e5) + (e6 * e6 + e7 * e7)); }
; #pragma unroll
;         for (int o = 1; o < 64; o <<= 1) {
; #pragma unroll
;             for (int q = 0; q < 4; ++q) rstd[q] += __shfl_xor(rstd[q], o); }
	v_and_b32_e32 v40, 0xffff0000, v17
	v_lshlrev_b32_e32 v43, 16, v13
	v_lshlrev_b32_e32 v42, 16, v17
	v_and_b32_e32 v45, 0xffff0000, v12
	v_and_b32_e32 v44, 0xffff0000, v16
	v_lshlrev_b32_e32 v13, 16, v12
	v_lshlrev_b32_e32 v12, 16, v16
	v_pk_fma_f32 v[48:49], v[22:23], s[12:13], v[48:49] op_sel_hi:[1,0,1] neg_lo:[1,0,0] neg_hi:[1,0,0]
	v_pk_add_f32 v[30:31], v[30:31], v[32:33]
	v_pk_mul_f32 v[32:33], v[64:65], v[64:65]
	v_pk_add_f32 v[46:47], v[42:43], v[40:41]
	v_pk_add_f32 v[16:17], v[12:13], v[44:45]
	v_pk_fma_f32 v[32:33], v[48:49], v[48:49], v[32:33]
	v_pk_add_f32 v[50:51], v[16:17], v[46:47]
	v_lshlrev_b32_e32 v17, 16, v11
	v_lshlrev_b32_e32 v16, 16, v15
	v_and_b32_e32 v47, 0xffff0000, v11
	v_and_b32_e32 v46, 0xffff0000, v15
	v_lshlrev_b32_e32 v49, 16, v10
	v_lshlrev_b32_e32 v48, 16, v14
	v_and_b32_e32 v11, 0xffff0000, v10
	v_and_b32_e32 v10, 0xffff0000, v14
	v_pk_add_f32 v[14:15], v[16:17], v[46:47]
	v_pk_add_f32 v[52:53], v[48:49], v[10:11]
	v_lshlrev_b32_e32 v55, 16, v5
	v_pk_add_f32 v[62:63], v[52:53], v[14:15]
	v_lshlrev_b32_e32 v15, 16, v4
	v_lshlrev_b32_e32 v14, 16, v8
	v_and_b32_e32 v53, 0xffff0000, v4
	v_and_b32_e32 v52, 0xffff0000, v8
	v_lshlrev_b32_e32 v54, 16, v9
	v_and_b32_e32 v5, 0xffff0000, v5
	v_and_b32_e32 v4, 0xffff0000, v9
	v_lshlrev_b32_e32 v9, 16, v2
	v_lshlrev_b32_e32 v8, 16, v6
	v_and_b32_e32 v65, 0xffff0000, v2
	v_and_b32_e32 v64, 0xffff0000, v6
	v_lshlrev_b32_e32 v67, 16, v3
	v_lshlrev_b32_e32 v66, 16, v7
	v_pk_add_f32 v[2:3], v[14:15], v[52:53]
	v_pk_add_f32 v[6:7], v[54:55], v[4:5]
	v_pk_add_f32 v[70:71], v[66:67], v[68:69]
	v_pk_add_f32 v[2:3], v[2:3], v[6:7]
	v_pk_add_f32 v[6:7], v[8:9], v[64:65]
	v_pk_fma_f32 v[24:25], v[24:25], v[24:25], v[34:35]
	v_pk_add_f32 v[6:7], v[6:7], v[70:71]
	v_pk_fma_f32 v[26:27], v[26:27], v[26:27], v[36:37]
	v_pk_add_f32 v[2:3], v[6:7], v[2:3]
	v_pk_add_f32 v[24:25], v[24:25], v[26:27]
	v_pk_add_f32 v[2:3], v[2:3], v[62:63]
	s_nop 0
	v_pk_add_f32 v[2:3], v[50:51], v[2:3]
	s_nop 1
	v_add_f32_dpp v2, v2, v2 quad_perm:[1,0,3,2] row_mask:0xf bank_mask:0xf
	v_add_f32_dpp v3, v3, v3 quad_perm:[1,0,3,2] row_mask:0xf bank_mask:0xf
	s_nop 0
	v_add_f32_dpp v2, v2, v2 quad_perm:[2,3,0,1] row_mask:0xf bank_mask:0xf
	v_add_f32_dpp v3, v3, v3 quad_perm:[2,3,0,1] row_mask:0xf bank_mask:0xf
	s_nop 0
	v_add_f32_dpp v2, v2, v2 row_half_mirror row_mask:0xf bank_mask:0xf
	v_add_f32_dpp v3, v3, v3 row_half_mirror row_mask:0xf bank_mask:0xf
	s_nop 0
	v_add_f32_dpp v2, v2, v2 row_mirror row_mask:0xf bank_mask:0xf
	v_add_f32_dpp v3, v3, v3 row_mirror row_mask:0xf bank_mask:0xf
	s_nop 0
	v_mov_b32_e32 v6, v2
	v_mov_b32_e32 v7, v3
	s_nop 1
	v_permlane16_swap_b32_e32 v2, v6
	v_permlane16_swap_b32_e32 v3, v7
	v_pk_add_f32 v[2:3], v[2:3], v[6:7]
	s_nop 0
	v_mov_b32_e32 v6, v2
	v_mov_b32_e32 v7, v3
	s_nop 1
	v_permlane32_swap_b32_e32 v2, v6
	v_permlane32_swap_b32_e32 v3, v7
	v_pk_add_f32 v[2:3], v[2:3], v[6:7]
	s_nop 0
	v_pk_fma_f32 v[6:7], v[2:3], s[12:13], v[8:9] op_sel_hi:[1,0,1] neg_lo:[1,0,0] neg_hi:[1,0,0]
	v_pk_fma_f32 v[8:9], v[2:3], s[12:13], v[64:65] op_sel_hi:[1,0,1] neg_lo:[1,0,0] neg_hi:[1,0,0]
	v_pk_fma_f32 v[62:63], v[2:3], s[12:13], v[68:69] op_sel_hi:[1,0,1] neg_lo:[1,0,0] neg_hi:[1,0,0]
	v_pk_mul_f32 v[8:9], v[8:9], v[8:9]
	v_pk_fma_f32 v[50:51], v[2:3], s[12:13], v[66:67] op_sel_hi:[1,0,1] neg_lo:[1,0,0] neg_hi:[1,0,0]
	v_pk_fma_f32 v[6:7], v[6:7], v[6:7], v[8:9]
	v_pk_mul_f32 v[8:9], v[62:63], v[62:63]
	v_pk_fma_f32 v[52:53], v[2:3], s[12:13], v[52:53] op_sel_hi:[1,0,1] neg_lo:[1,0,0] neg_hi:[1,0,0]
	v_pk_fma_f32 v[4:5], v[2:3], s[12:13], v[4:5] op_sel_hi:[1,0,1] neg_lo:[1,0,0] neg_hi:[1,0,0]
	v_pk_fma_f32 v[8:9], v[50:51], v[50:51], v[8:9]
	v_pk_fma_f32 v[14:15], v[2:3], s[12:13], v[14:15] op_sel_hi:[1,0,1] neg_lo:[1,0,0] neg_hi:[1,0,0]
	v_pk_fma_f32 v[54:55], v[2:3], s[12:13], v[54:55] op_sel_hi:[1,0,1] neg_lo:[1,0,0] neg_hi:[1,0,0]
	v_pk_add_f32 v[6:7], v[6:7], v[8:9]
	v_pk_mul_f32 v[8:9], v[52:53], v[52:53]
	v_pk_mul_f32 v[4:5], v[4:5], v[4:5]
	v_pk_fma_f32 v[10:11], v[2:3], s[12:13], v[10:11] op_sel_hi:[1,0,1] neg_lo:[1,0,0] neg_hi:[1,0,0]
	v_pk_fma_f32 v[8:9], v[14:15], v[14:15], v[8:9]
	v_pk_fma_f32 v[4:5], v[54:55], v[54:55], v[4:5]
	v_pk_fma_f32 v[48:49], v[2:3], s[12:13], v[48:49] op_sel_hi:[1,0,1] neg_lo:[1,0,0] neg_hi:[1,0,0]
	v_pk_fma_f32 v[46:47], v[2:3], s[12:13], v[46:47] op_sel_hi:[1,0,1] neg_lo:[1,0,0] neg_hi:[1,0,0]
	v_pk_add_f32 v[8:9], v[8:9], v[4:5]
	v_pk_mul_f32 v[4:5], v[10:11], v[10:11]
	v_pk_fma_f32 v[16:17], v[2:3], s[12:13], v[16:17] op_sel_hi:[1,0,1] neg_lo:[1,0,0] neg_hi:[1,0,0]
	v_pk_fma_f32 v[10:11], v[48:49], v[48:49], v[4:5]
	v_pk_mul_f32 v[4:5], v[46:47], v[46:47]
	v_pk_fma_f32 v[44:45], v[2:3], s[12:13], v[44:45] op_sel_hi:[1,0,1] neg_lo:[1,0,0] neg_hi:[1,0,0]
	v_pk_fma_f32 v[40:41], v[2:3], s[12:13], v[40:41] op_sel_hi:[1,0,1] neg_lo:[1,0,0] neg_hi:[1,0,0]
	v_pk_fma_f32 v[14:15], v[16:17], v[16:17], v[4:5]
	v_pk_fma_f32 v[12:13], v[2:3], s[12:13], v[12:13] op_sel_hi:[1,0,1] neg_lo:[1,0,0] neg_hi:[1,0,0]
	v_pk_fma_f32 v[42:43], v[2:3], s[12:13], v[42:43] op_sel_hi:[1,0,1] neg_lo:[1,0,0] neg_hi:[1,0,0]
	v_pk_mul_f32 v[16:17], v[44:45], v[44:45]
	v_pk_mul_f32 v[40:41], v[40:41], v[40:41]
	v_pk_add_f32 v[6:7], v[6:7], v[8:9]
	v_pk_add_f32 v[8:9], v[10:11], v[14:15]
	v_pk_add_f32 v[4:5], v[28:29], v[30:31]
	v_pk_add_f32 v[28:29], v[32:33], v[38:39]
	v_pk_add_f32 v[6:7], v[8:9], v[6:7]
	v_pk_fma_f32 v[8:9], v[12:13], v[12:13], v[16:17]
	v_pk_fma_f32 v[10:11], v[42:43], v[42:43], v[40:41]
	v_pk_add_f32 v[4:5], v[28:29], v[4:5]
	v_pk_add_f32 v[8:9], v[8:9], v[10:11]
	v_pk_add_f32 v[4:5], v[24:25], v[4:5]
	v_pk_add_f32 v[6:7], v[8:9], v[6:7]
	ds_bpermute_b32 v25, v56, v5
	ds_bpermute_b32 v24, v56, v4
	ds_bpermute_b32 v9, v56, v7
	ds_bpermute_b32 v8, v56, v6
	s_waitcnt lgkmcnt(2)
	v_pk_add_f32 v[4:5], v[4:5], v[24:25]
	ds_bpermute_b32 v25, v57, v5
	s_waitcnt lgkmcnt(1)
	v_pk_add_f32 v[6:7], v[6:7], v[8:9]
	ds_bpermute_b32 v24, v57, v4
	ds_bpermute_b32 v9, v57, v7
	ds_bpermute_b32 v8, v57, v6
	s_waitcnt lgkmcnt(2)
	v_pk_add_f32 v[4:5], v[4:5], v[24:25]
	ds_bpermute_b32 v25, v58, v5
	s_waitcnt lgkmcnt(1)
	v_pk_add_f32 v[6:7], v[6:7], v[8:9]
	ds_bpermute_b32 v24, v58, v4
	ds_bpermute_b32 v9, v58, v7
	ds_bpermute_b32 v8, v58, v6
	s_waitcnt lgkmcnt(2)
	v_pk_add_f32 v[4:5], v[4:5], v[24:25]
	ds_bpermute_b32 v25, v59, v5
	s_waitcnt lgkmcnt(1)
	v_pk_add_f32 v[6:7], v[6:7], v[8:9]
	ds_bpermute_b32 v24, v59, v4
	ds_bpermute_b32 v9, v59, v7
	ds_bpermute_b32 v8, v59, v6
	s_waitcnt lgkmcnt(2)
	v_pk_add_f32 v[4:5], v[4:5], v[24:25]
	ds_bpermute_b32 v25, v60, v5
	s_waitcnt lgkmcnt(1)
	v_pk_add_f32 v[6:7], v[6:7], v[8:9]
	ds_bpermute_b32 v24, v60, v4
	ds_bpermute_b32 v9, v60, v7
	ds_bpermute_b32 v8, v60, v6
	s_waitcnt lgkmcnt(2)
	v_pk_add_f32 v[4:5], v[4:5], v[24:25]
	ds_bpermute_b32 v11, v61, v5
	s_waitcnt lgkmcnt(1)
	v_pk_add_f32 v[6:7], v[6:7], v[8:9]
	ds_bpermute_b32 v10, v61, v4
	ds_bpermute_b32 v9, v61, v7
	ds_bpermute_b32 v8, v61, v6
	s_and_saveexec_b64 s[88:89], s[40:41]
	s_cbranch_execz .LBB0_519
; __device__ __forceinline__ void sgu_item(KP p, LAS unsigned char* lds, int l, int n) {
;     ...
;             for (int q = 0; q < 4; ++q) rstd[q] += __shfl_xor(rstd[q], o); }
;         if (lane == 0) {
; #pragma unroll
;             for (int q = 0; q < 4; ++q) { stats[(wid * 16 + tb + q) * 2] = mean[q]; stats[(wid * 16 + tb + q) * 2 + 1] = rsqrtf(rstd[q] * (1.f / 1024.f) + LN_EPS); } }
	s_mov_b32 s24, 0x3727c5ac
	s_waitcnt lgkmcnt(2)
	v_pk_add_f32 v[4:5], v[4:5], v[10:11]
	v_mov_b64_e32 v[14:15], s[24:25]
	v_pk_fma_f32 v[4:5], v[4:5], s[12:13], v[14:15] op_sel_hi:[1,0,0]
	v_pk_mul_f32 v[12:13], v[22:23], s[12:13] op_sel_hi:[1,0]
	v_mul_f32_e32 v10, 0x4b800000, v5
	v_cmp_gt_f32_e32 vcc, s56, v5
	v_cmp_gt_f32_e64 s[42:43], s56, v4
	s_nop 0
	v_cndmask_b32_e32 v5, v5, v10, vcc
	v_rsq_f32_e32 v10, v5
	v_mul_f32_e32 v5, 0x4b800000, v4
	v_cndmask_b32_e64 v4, v4, v5, s[42:43]
	v_rsq_f32_e32 v16, v4
	v_pk_mul_f32 v[4:5], v[2:3], s[12:13] op_sel_hi:[1,0]
	v_mul_f32_e32 v2, 0x45800000, v10
	v_cndmask_b32_e32 v11, v10, v2, vcc
	v_mul_f32_e32 v2, 0x45800000, v16
	v_cndmask_b32_e64 v2, v16, v2, s[42:43]
	v_mov_b32_e32 v10, v13
	v_mov_b32_e32 v13, v2
	s_waitcnt lgkmcnt(0)
	v_pk_add_f32 v[2:3], v[6:7], v[8:9]
	v_mov_b32_e32 v16, s61
	v_pk_fma_f32 v[2:3], v[2:3], s[12:13], v[14:15] op_sel_hi:[1,0,0]
	ds_write_b128 v16, v[10:13]
	v_mul_f32_e32 v6, 0x4b800000, v3
	v_cmp_gt_f32_e32 vcc, s56, v3
	v_cmp_gt_f32_e64 s[42:43], s56, v2
	s_nop 0
	v_cndmask_b32_e32 v3, v3, v6, vcc
	v_mul_f32_e32 v6, 0x4b800000, v2
	v_rsq_f32_e32 v3, v3
	v_cndmask_b32_e64 v2, v2, v6, s[42:43]
	v_rsq_f32_e32 v2, v2
	v_mul_f32_e32 v6, 0x45800000, v3
	v_cndmask_b32_e32 v3, v3, v6, vcc
	v_mul_f32_e32 v6, 0x45800000, v2
	v_cndmask_b32_e64 v6, v2, v6, s[42:43]
	v_mov_b32_e32 v2, v5
	v_mov_b32_e32 v5, v6
	ds_write_b128 v16, v[2:5] offset:16
	s_branch .LBB0_519
